# v086 with the eight vector prep ops placed in MFMA gaps 0-3 (no conversions there) instead of gaps 4-11: cost-weighted VALU spacing
# speedup vs baseline: 1.0016x; 1.0006x over previous
; #define ALAS __attribute__((address_space(3)))
; template <int N> __device__ __forceinline__ void wait_bar() { asm volatile("s_waitcnt vmcnt(%0) lgkmcnt(0)\n\ts_barrier" :: "n"(N) : "memory"); }
; template <bool WIN> ...
;     ...
;     for (int tr = 0; tr < NT; ++tr) {
;         if (tr + 2 < NT) wait_bar<2 * NPW>(); else if (tr + 1 < NT) wait_bar<NPW>(); else wait_bar<0>();
;         if (tr + 3 < NT) AT_DMA(tr + 3);
;         const int k0 = (t_lo + tr) * 64;
;         const bool skip = WIN && (k0 > qw + 31 + 128 || k0 + 63 < qw - 128);
;         if (!skip) {
;             const bool near = WIN || ((k0 - (qw + 31)) < 128 && (qw - (k0 + 63)) < 128);
;             const float cinit = near ? 0.f : (k0 > qw ? cfar_hi : cfar_lo);
;     ...
;             float ls0 = 0.f, ls1 = 0.f;
;     ...
;             union PFU { u32x4 u; bf16x8 b; };
;             PFU p0, p1, p2, p3;
;             AT_EXP(s0, 0, p0);
; #pragma unroll
;             for (int kk = 0; kk < 2; ++kk)
; #pragma unroll
;                 for (int db = 0; db < NDB; ++db) vc[kk * NDB + db] = *(const ALAS bf16x8*)(sb + vx[kk + 2] + db * 4096);
;             __builtin_amdgcn_sched_barrier(0);
; #pragma unroll
;             for (int db = 0; db < NDB; ++db) o[db] = __builtin_amdgcn_mfma_f32_32x32x16_bf16(va[db], p0.b, o[db], 0, 0, 0);
;             AT_EXP(s0, 8, p1);
;             __builtin_amdgcn_sched_barrier(0);
; #pragma unroll
;             for (int db = 0; db < NDB; ++db) o[db] = __builtin_amdgcn_mfma_f32_32x32x16_bf16(va[NDB + db], p1.b, o[db], 0, 0, 0);
;             AT_EXP(s1, 0, p2);
;             __builtin_amdgcn_sched_barrier(0);
; #pragma unroll
;             for (int db = 0; db < NDB; ++db) o[db] = __builtin_amdgcn_mfma_f32_32x32x16_bf16(vc[db], p2.b, o[db], 0, 0, 0);
;             AT_EXP(s1, 8, p3);
;             __builtin_amdgcn_sched_barrier(0);
; #pragma unroll
;             for (int db = 0; db < NDB; ++db) o[db] = __builtin_amdgcn_mfma_f32_32x32x16_bf16(vc[NDB + db], p3.b, o[db], 0, 0, 0);
;             __builtin_amdgcn_sched_barrier(0);
;     ...
;             l_run += ls0 + ls1;
.LSPp_pv:
	s_cmp_eq_u32 s86, 0
	s_cbranch_scc1 .LSPp_pure
	s_waitcnt lgkmcnt(4)
	v_mfma_f32_32x32x16_bf16 v[50:65], v[130:133], v[238:241], v[50:65]
	v_exp_f32_e32 v98, v98
	v_exp_f32_e32 v99, v99
	s_add_i32 s87, s85, 0xffff8000
	s_and_b32 s87, s87, 0x18000
	v_lshl_add_u64 v[174:175], v[174:175], 0, s[60:61]
	v_lshl_add_u64 v[172:173], v[172:173], 0, s[48:49]
	v_mfma_f32_32x32x16_bf16 v[34:49], v[134:137], v[238:241], v[34:49]
	v_exp_f32_e32 v100, v100
	v_exp_f32_e32 v101, v101
	v_lshl_add_u64 v[208:209], v[174:175], 0, s[40:41]
	v_lshl_add_u64 v[210:211], v[172:173], 0, s[40:41]
	v_mfma_f32_32x32x16_bf16 v[18:33], v[138:141], v[238:241], v[18:33]
	v_exp_f32_e32 v102, v102
	v_exp_f32_e32 v103, v103
	v_add_f32_e32 v228, v98, v100
	v_add_f32_e32 v229, v99, v101
	v_add3_u32 v212, s87, v178, v162
	v_add3_u32 v213, s87, v180, v162
	v_mfma_f32_32x32x16_bf16 v[2:17], v[142:145], v[238:241], v[2:17]
	v_exp_f32_e32 v104, v104
	v_exp_f32_e32 v105, v105
	v_add_f32_e32 v228, v228, v102
	v_add_f32_e32 v229, v229, v103
	v_add3_u32 v214, s87, v182, v162
	v_add3_u32 v215, s87, v184, v162
	v_add3_u32 v236, s99, v183, v187
	ds_read_b128 v[130:133], v236 offset:16384
	ds_read_b128 v[134:137], v236 offset:20480
	ds_read_b128 v[138:141], v236 offset:24576
	ds_read_b128 v[142:145], v236 offset:28672
	s_waitcnt lgkmcnt(4)
	v_mfma_f32_32x32x16_bf16 v[50:65], v[146:149], v[242:245], v[50:65]
	v_exp_f32_e32 v106, v106
	v_exp_f32_e32 v107, v107
	v_add_f32_e32 v228, v228, v104
	v_add_f32_e32 v229, v229, v105
	v_cvt_pk_bf16_f32 v238, v98, v99
	s_add_i32 s98, s85, 0x10000
	s_and_b32 s98, s98, 0x18000
	v_mfma_f32_32x32x16_bf16 v[34:49], v[150:153], v[242:245], v[34:49]
	v_exp_f32_e32 v108, v108
	v_exp_f32_e32 v109, v109
	v_add_f32_e32 v228, v228, v106
	v_add_f32_e32 v229, v229, v107
	v_cvt_pk_bf16_f32 v239, v100, v101
	s_add_i32 s98, s98, s20
	s_add_i32 s101, s85, 0x8000
	v_mfma_f32_32x32x16_bf16 v[18:33], v[154:157], v[242:245], v[18:33]
	v_exp_f32_e32 v110, v110
	v_exp_f32_e32 v111, v111
	v_add_f32_e32 v228, v228, v108
	v_add_f32_e32 v229, v229, v109
	v_cvt_pk_bf16_f32 v240, v102, v103
	s_and_b32 s101, s101, 0x18000
	s_add_i32 s101, s101, s20
	v_mfma_f32_32x32x16_bf16 v[2:17], v[158:161], v[242:245], v[2:17]
	v_exp_f32_e32 v112, v112
	v_exp_f32_e32 v113, v113
	v_add_f32_e32 v228, v228, v110
	v_add_f32_e32 v229, v229, v111
	v_cvt_pk_bf16_f32 v241, v104, v105
	v_add3_u32 v237, s99, v190, v187
	ds_read_b128 v[146:149], v237 offset:16384
	ds_read_b128 v[150:153], v237 offset:20480
	ds_read_b128 v[154:157], v237 offset:24576
	ds_read_b128 v[158:161], v237 offset:28672
	s_waitcnt lgkmcnt(4)
	v_mfma_f32_32x32x16_bf16 v[50:65], v[130:133], v[246:249], v[50:65]
	v_exp_f32_e32 v82, v82
	v_exp_f32_e32 v83, v83
	v_add_f32_e32 v228, v228, v112
	v_add_f32_e32 v229, v229, v113
	v_cvt_pk_bf16_f32 v242, v106, v107
	s_add_i32 s99, s81, s83
	s_add_i32 s99, s99, 64
	v_mfma_f32_32x32x16_bf16 v[34:49], v[134:137], v[246:249], v[34:49]
	v_exp_f32_e32 v84, v84
	v_exp_f32_e32 v85, v85
	v_add_f32_e32 v228, v228, v82
	v_add_f32_e32 v229, v229, v83
	v_cvt_pk_bf16_f32 v243, v108, v109
	s_sub_i32 m0, s82, 64
	s_max_i32 s99, s99, m0
	v_mfma_f32_32x32x16_bf16 v[18:33], v[138:141], v[246:249], v[18:33]
	v_exp_f32_e32 v86, v86
	v_exp_f32_e32 v87, v87
	v_add_f32_e32 v228, v228, v84
	v_add_f32_e32 v229, v229, v85
	v_cvt_pk_bf16_f32 v244, v110, v111
	s_add_i32 m0, s83, 64
	s_cmp_gt_i32 m0, s78
	v_mfma_f32_32x32x16_bf16 v[2:17], v[142:145], v[246:249], v[2:17]
	v_exp_f32_e32 v88, v88
	v_exp_f32_e32 v89, v89
	v_add_f32_e32 v228, v228, v86
	v_add_f32_e32 v229, v229, v87
	v_cvt_pk_bf16_f32 v245, v112, v113
	s_cselect_b32 m0, s80, s79
	s_cmpk_lt_i32 s99, 0x80
	s_waitcnt lgkmcnt(0)
	v_mfma_f32_32x32x16_bf16 v[50:65], v[146:149], v[250:253], v[50:65]
	v_exp_f32_e32 v90, v90
	v_exp_f32_e32 v91, v91
	v_add_f32_e32 v228, v228, v88
	v_add_f32_e32 v229, v229, v89
	v_cvt_pk_bf16_f32 v246, v82, v83
	s_cselect_b32 s65, 1, 0
	s_cselect_b32 m0, 0, m0
	v_mfma_f32_32x32x16_bf16 v[34:49], v[150:153], v[250:253], v[34:49]
	v_exp_f32_e32 v92, v92
	v_exp_f32_e32 v93, v93
	v_add_f32_e32 v228, v228, v90
	v_add_f32_e32 v229, v229, v91
	v_cvt_pk_bf16_f32 v247, v84, v85
	s_add_i32 s99, s85, 0xffff0000
	s_and_b32 s99, s99, 0x18000
	v_mfma_f32_32x32x16_bf16 v[18:33], v[154:157], v[250:253], v[18:33]
	v_exp_f32_e32 v94, v94
	v_exp_f32_e32 v95, v95
	v_add_f32_e32 v228, v228, v92
	v_add_f32_e32 v229, v229, v93
	v_cvt_pk_bf16_f32 v248, v86, v87
	v_mfma_f32_32x32x16_bf16 v[2:17], v[158:161], v[250:253], v[2:17]
	v_exp_f32_e32 v96, v96
	v_exp_f32_e32 v97, v97
	v_add_f32_e32 v228, v228, v94
	v_add_f32_e32 v229, v229, v95
	v_cvt_pk_bf16_f32 v249, v88, v89
	v_add_f32_e32 v228, v228, v96
	v_add_f32_e32 v229, v229, v97
	v_cvt_pk_bf16_f32 v250, v90, v91
	v_cvt_pk_bf16_f32 v251, v92, v93
	v_cvt_pk_bf16_f32 v252, v94, v95
	v_cvt_pk_bf16_f32 v253, v96, v97
	ds_read_b128 v[130:133], v212
	ds_read_b128 v[134:137], v212 offset:4096
	ds_read_b128 v[138:141], v213
	ds_read_b128 v[142:145], v213 offset:4096
	ds_read_b128 v[146:149], v214
	ds_read_b128 v[150:153], v214 offset:4096
	ds_read_b128 v[158:161], v215
	ds_read_b128 v[204:207], v215 offset:4096
	v_add_f32_e32 v228, v228, v229
	v_cmp_nge_f32_e32 vcc, 0x53800000, v228
	s_cbranch_vccnz .LSPp_redo
	s_add_i32 s86, s86, 1
	s_add_i32 s85, s85, 0x8000
	s_addk_i32 s84, 0x100
	s_add_i32 s83, s83, 64
	s_sub_i32 s82, s82, 64
	v_add_f32_e32 v0, v0, v228
	s_cmpk_eq_u32 s84, 0x8000
	s_cbranch_scc0 .LSPp_top
	s_branch .LSPp_exit

; #define ALAS __attribute__((address_space(3)))
; template <int N> __device__ __forceinline__ void wait_bar() { asm volatile("s_waitcnt vmcnt(%0) lgkmcnt(0)\n\ts_barrier" :: "n"(N) : "memory"); }
; template <bool WIN> ...
;     ...
;     for (int tr = 0; tr < NT; ++tr) {
;         if (tr + 2 < NT) wait_bar<2 * NPW>(); else if (tr + 1 < NT) wait_bar<NPW>(); else wait_bar<0>();
;         if (tr + 3 < NT) AT_DMA(tr + 3);
;         const int k0 = (t_lo + tr) * 64;
;         const bool skip = WIN && (k0 > qw + 31 + 128 || k0 + 63 < qw - 128);
;         if (!skip) {
;             const bool near = WIN || ((k0 - (qw + 31)) < 128 && (qw - (k0 + 63)) < 128);
;             const float cinit = near ? 0.f : (k0 > qw ? cfar_hi : cfar_lo);
;     ...
;             float ls0 = 0.f, ls1 = 0.f;
;     ...
;             union PFU { u32x4 u; bf16x8 b; };
;             PFU p0, p1, p2, p3;
;             AT_EXP(s0, 0, p0);
; #pragma unroll
;             for (int kk = 0; kk < 2; ++kk)
; #pragma unroll
;                 for (int db = 0; db < NDB; ++db) vc[kk * NDB + db] = *(const ALAS bf16x8*)(sb + vx[kk + 2] + db * 4096);
;             __builtin_amdgcn_sched_barrier(0);
; #pragma unroll
;             for (int db = 0; db < NDB; ++db) o[db] = __builtin_amdgcn_mfma_f32_32x32x16_bf16(va[db], p0.b, o[db], 0, 0, 0);
;             AT_EXP(s0, 8, p1);
;             __builtin_amdgcn_sched_barrier(0);
; #pragma unroll
;             for (int db = 0; db < NDB; ++db) o[db] = __builtin_amdgcn_mfma_f32_32x32x16_bf16(va[NDB + db], p1.b, o[db], 0, 0, 0);
;             AT_EXP(s1, 0, p2);
;             __builtin_amdgcn_sched_barrier(0);
; #pragma unroll
;             for (int db = 0; db < NDB; ++db) o[db] = __builtin_amdgcn_mfma_f32_32x32x16_bf16(vc[db], p2.b, o[db], 0, 0, 0);
;             AT_EXP(s1, 8, p3);
;             __builtin_amdgcn_sched_barrier(0);
; #pragma unroll
;             for (int db = 0; db < NDB; ++db) o[db] = __builtin_amdgcn_mfma_f32_32x32x16_bf16(vc[NDB + db], p3.b, o[db], 0, 0, 0);
;             __builtin_amdgcn_sched_barrier(0);
;     ...
;             l_run += ls0 + ls1;
.LSPs_pv:
	s_cmp_eq_u32 s79, 0
	s_cbranch_scc1 .LSPs_pure
	s_waitcnt lgkmcnt(4)
	v_mfma_f32_32x32x16_bf16 v[50:65], v[130:133], v[238:241], v[50:65]
	v_exp_f32_e32 v98, v98
	v_exp_f32_e32 v99, v99
	s_add_i32 s80, s78, 0xffff8000
	s_and_b32 s80, s80, 0x18000
	v_lshl_add_u64 v[174:175], v[174:175], 0, s[60:61]
	v_lshl_add_u64 v[172:173], v[172:173], 0, s[48:49]
	v_mfma_f32_32x32x16_bf16 v[34:49], v[134:137], v[238:241], v[34:49]
	v_exp_f32_e32 v100, v100
	v_exp_f32_e32 v101, v101
	v_lshl_add_u64 v[208:209], v[174:175], 0, s[40:41]
	v_lshl_add_u64 v[210:211], v[172:173], 0, s[40:41]
	v_mfma_f32_32x32x16_bf16 v[18:33], v[138:141], v[238:241], v[18:33]
	v_exp_f32_e32 v102, v102
	v_exp_f32_e32 v103, v103
	v_add_f32_e32 v228, v98, v100
	v_add_f32_e32 v229, v99, v101
	v_add3_u32 v212, s80, v178, v162
	v_add3_u32 v213, s80, v180, v162
	v_mfma_f32_32x32x16_bf16 v[2:17], v[142:145], v[238:241], v[2:17]
	v_exp_f32_e32 v104, v104
	v_exp_f32_e32 v105, v105
	v_add_f32_e32 v228, v228, v102
	v_add_f32_e32 v229, v229, v103
	v_add3_u32 v214, s80, v182, v162
	v_add3_u32 v215, s80, v184, v162
	v_add3_u32 v236, s99, v183, v187
	ds_read_b128 v[130:133], v236 offset:16384
	ds_read_b128 v[134:137], v236 offset:20480
	ds_read_b128 v[138:141], v236 offset:24576
	ds_read_b128 v[142:145], v236 offset:28672
	s_waitcnt lgkmcnt(4)
	v_mfma_f32_32x32x16_bf16 v[50:65], v[146:149], v[242:245], v[50:65]
	v_exp_f32_e32 v106, v106
	v_exp_f32_e32 v107, v107
	v_add_f32_e32 v228, v228, v104
	v_add_f32_e32 v229, v229, v105
	v_cvt_pk_bf16_f32 v238, v98, v99
	s_add_i32 s98, s78, 0x10000
	s_and_b32 s98, s98, 0x18000
	v_mfma_f32_32x32x16_bf16 v[34:49], v[150:153], v[242:245], v[34:49]
	v_exp_f32_e32 v108, v108
	v_exp_f32_e32 v109, v109
	v_add_f32_e32 v228, v228, v106
	v_add_f32_e32 v229, v229, v107
	v_cvt_pk_bf16_f32 v239, v100, v101
	s_add_i32 s98, s98, s29
	s_add_i32 s101, s78, 0x8000
	v_mfma_f32_32x32x16_bf16 v[18:33], v[154:157], v[242:245], v[18:33]
	v_exp_f32_e32 v110, v110
	v_exp_f32_e32 v111, v111
	v_add_f32_e32 v228, v228, v108
	v_add_f32_e32 v229, v229, v109
	v_cvt_pk_bf16_f32 v240, v102, v103
	s_and_b32 s101, s101, 0x18000
	s_add_i32 s101, s101, s29
	v_mfma_f32_32x32x16_bf16 v[2:17], v[158:161], v[242:245], v[2:17]
	v_exp_f32_e32 v112, v112
	v_exp_f32_e32 v113, v113
	v_add_f32_e32 v228, v228, v110
	v_add_f32_e32 v229, v229, v111
	v_cvt_pk_bf16_f32 v241, v104, v105
	v_add3_u32 v237, s99, v190, v187
	ds_read_b128 v[146:149], v237 offset:16384
	ds_read_b128 v[150:153], v237 offset:20480
	ds_read_b128 v[154:157], v237 offset:24576
	ds_read_b128 v[158:161], v237 offset:28672
	s_waitcnt lgkmcnt(4)
	v_mfma_f32_32x32x16_bf16 v[50:65], v[130:133], v[246:249], v[50:65]
	v_exp_f32_e32 v82, v82
	v_exp_f32_e32 v83, v83
	v_add_f32_e32 v228, v228, v112
	v_add_f32_e32 v229, v229, v113
	v_cvt_pk_bf16_f32 v242, v106, v107
	s_add_i32 s99, s76, 64
	s_cmp_gt_u32 s99, s28
	v_mfma_f32_32x32x16_bf16 v[34:49], v[134:137], v[246:249], v[34:49]
	v_exp_f32_e32 v84, v84
	v_exp_f32_e32 v85, v85
	v_add_f32_e32 v228, v228, v82
	v_add_f32_e32 v229, v229, v83
	v_cvt_pk_bf16_f32 v243, v108, v109
	s_cselect_b32 m0, s31, s30
	s_cmp_lt_u32 s99, s33
	v_mfma_f32_32x32x16_bf16 v[18:33], v[138:141], v[246:249], v[18:33]
	v_exp_f32_e32 v86, v86
	v_exp_f32_e32 v87, v87
	v_add_f32_e32 v228, v228, v84
	v_add_f32_e32 v229, v229, v85
	v_cvt_pk_bf16_f32 v244, v110, v111
	s_cselect_b32 s65, 1, 0
	s_cmp_gt_i32 s99, s67
	v_mfma_f32_32x32x16_bf16 v[2:17], v[142:145], v[246:249], v[2:17]
	v_exp_f32_e32 v88, v88
	v_exp_f32_e32 v89, v89
	v_add_f32_e32 v228, v228, v86
	v_add_f32_e32 v229, v229, v87
	v_cvt_pk_bf16_f32 v245, v112, v113
	s_cselect_b32 s65, s65, 0
	s_cmp_lg_u32 s65, 0
	s_waitcnt lgkmcnt(0)
	v_mfma_f32_32x32x16_bf16 v[50:65], v[146:149], v[250:253], v[50:65]
	v_exp_f32_e32 v90, v90
	v_exp_f32_e32 v91, v91
	v_add_f32_e32 v228, v228, v88
	v_add_f32_e32 v229, v229, v89
	v_cvt_pk_bf16_f32 v246, v82, v83
	s_cselect_b32 m0, 0, m0
	s_add_i32 s99, s78, 0xffff0000
	v_mfma_f32_32x32x16_bf16 v[34:49], v[150:153], v[250:253], v[34:49]
	v_exp_f32_e32 v92, v92
	v_exp_f32_e32 v93, v93
	v_add_f32_e32 v228, v228, v90
	v_add_f32_e32 v229, v229, v91
	v_cvt_pk_bf16_f32 v247, v84, v85
	s_and_b32 s99, s99, 0x18000
	v_mfma_f32_32x32x16_bf16 v[18:33], v[154:157], v[250:253], v[18:33]
	v_exp_f32_e32 v94, v94
	v_exp_f32_e32 v95, v95
	v_add_f32_e32 v228, v228, v92
	v_add_f32_e32 v229, v229, v93
	v_cvt_pk_bf16_f32 v248, v86, v87
	v_mfma_f32_32x32x16_bf16 v[2:17], v[158:161], v[250:253], v[2:17]
	v_exp_f32_e32 v96, v96
	v_exp_f32_e32 v97, v97
	v_add_f32_e32 v228, v228, v94
	v_add_f32_e32 v229, v229, v95
	v_cvt_pk_bf16_f32 v249, v88, v89
	v_add_f32_e32 v228, v228, v96
	v_add_f32_e32 v229, v229, v97
	v_cvt_pk_bf16_f32 v250, v90, v91
	v_cvt_pk_bf16_f32 v251, v92, v93
	v_cvt_pk_bf16_f32 v252, v94, v95
	v_cvt_pk_bf16_f32 v253, v96, v97
	ds_read_b128 v[130:133], v212
	ds_read_b128 v[134:137], v212 offset:4096
	ds_read_b128 v[138:141], v213
	ds_read_b128 v[142:145], v213 offset:4096
	ds_read_b128 v[146:149], v214
	ds_read_b128 v[150:153], v214 offset:4096
	ds_read_b128 v[158:161], v215
	ds_read_b128 v[204:207], v215 offset:4096
	v_add_f32_e32 v228, v228, v229
	v_cmp_nge_f32_e32 vcc, 0x53800000, v228
	s_cbranch_vccnz .LSPs_redo
	s_add_i32 s79, s79, 1
	s_add_i32 s78, s78, 0x8000
	s_addk_i32 s77, 0x100
	s_add_i32 s76, s76, 64
	v_add_f32_e32 v0, v0, v228
	s_cmpk_eq_i32 s77, 0x2000
	s_cbranch_scc0 .LSPs_top
	s_branch .LSPs_exit
